# v30 + SB unit: Q-fragment loads waited once at the end of the unit prologue; QK^T waits no longer carry vmcnt (they also drained the per-tile K/V prefetch loads)
# speedup vs baseline: 1.0029x; 1.0024x over previous
.LBB0_656:
	s_or_b64 exec, exec, s[4:5]
	v_readlane_b32 s4, v255, 24
	s_waitcnt lgkmcnt(0)
	s_barrier
	v_mov_b32_e32 v1, s4
	ds_read_b32 v1, v1
	s_mov_b64 s[4:5], -1
	s_waitcnt lgkmcnt(0)
	s_barrier
	v_readfirstlane_b32 s8, v1
	s_cmpk_gt_i32 s8, 0x5f
	s_cbranch_scc1 .LBB0_651
	s_mul_hi_i32 s4, s8, 0xd5555555
	s_lshr_b32 s5, s4, 31
	s_ashr_i32 s21, s4, 1
	s_mul_hi_i32 s4, s8, 0x2aaaaaab
	s_add_i32 s21, s21, s5
	s_lshr_b32 s5, s4, 31
	s_lshr_b32 s4, s4, 1
	s_add_i32 s4, s4, s5
	s_mul_i32 s4, s4, 12
	s_sub_i32 s4, s8, s4
	s_lshl_b32 s4, s4, 3
	s_or_b32 s4, s4, s52
	s_mul_hi_i32 s5, s4, 0x2aaaaaab
	s_lshr_b32 s8, s5, 31
	s_add_i32 s12, s5, s8
	s_mul_i32 s5, s12, 6
	v_mov_b32_e32 v1, v0
	s_sub_i32 s4, s4, s5
	s_add_i32 s20, s21, 7
	v_readfirstlane_b32 s5, v1
	s_ashr_i32 s25, s5, 6
	s_lshl_b32 s5, s20, 8
	s_lshl_b32 s28, s25, 5
	s_ashr_i32 s13, s12, 31
	s_lshl_b32 s18, s4, 23
	s_add_i32 s9, s28, s5
	s_lshl_b64 s[10:11], s[12:13], 11
	s_lshl_b32 s8, s4, 7
	s_add_i32 s5, s18, 0x6000000
	v_readlane_b32 s30, v254, 52
	v_readlane_b32 s31, v254, 53
	s_add_u32 s22, s30, s5
	s_addc_u32 s23, s31, 0
	s_bfe_i64 s[4:5], s[4:5], 0x100000
	s_lshl_b64 s[4:5], s[4:5], 23
	s_add_u32 s4, s30, s4
	s_addc_u32 s5, s31, s5
	s_add_i32 s18, s18, 0x3000000
	s_add_u32 s18, s30, s18
	s_addc_u32 s19, s31, 0
	s_lshl_b64 s[12:13], s[12:13], 19
	s_add_u32 s18, s18, s12
	s_addc_u32 s19, s19, s13
	s_add_u32 s22, s22, s12
	s_addc_u32 s23, s23, s13
	s_lshl_b32 s13, s20, 2
	v_ashrrev_i32_e32 v163, 4, v1
	s_or_b32 s12, s13, 3
	v_lshlrev_b32_e32 v8, 3, v1
	v_lshl_add_u32 v2, s12, 6, v163
	v_and_b32_e32 v162, 0x78, v8
	v_ashrrev_i32_e32 v3, 31, v2
	v_lshlrev_b32_e32 v9, 1, v162
	v_lshlrev_b64 v[2:3], 8, v[2:3]
	v_or_b32_e32 v2, v2, v9
	v_lshl_add_u64 v[4:5], s[18:19], 0, v[2:3]
	s_movk_i32 s20, 0x2000
	v_add_co_u32_e32 v6, vcc, s20, v4
	v_lshl_add_u64 v[2:3], s[22:23], 0, v[2:3]
	s_nop 0
	v_addc_co_u32_e32 v7, vcc, 0, v5, vcc
	global_load_dwordx4 v[114:117], v[4:5], off
	global_load_dwordx4 v[118:121], v[6:7], off
	global_load_dwordx4 v[150:153], v[2:3], off
	v_add_co_u32_e32 v2, vcc, s20, v2
	v_and_b32_e32 v186, 31, v1
	s_nop 0
	v_addc_co_u32_e32 v3, vcc, 0, v3, vcc
	global_load_dwordx4 v[158:161], v[2:3], off
	v_or_b32_e32 v2, s9, v186
	v_ashrrev_i32_e32 v3, 31, v2
	v_lshl_add_u64 v[2:3], s[10:11], 0, v[2:3]
	v_bfe_u32 v187, v1, 5, 1
	v_lshlrev_b64 v[2:3], 8, v[2:3]
	v_lshl_add_u64 v[2:3], s[4:5], 0, v[2:3]
	v_lshlrev_b32_e32 v34, 4, v187
	v_lshl_add_u64 v[2:3], v[2:3], 0, v[34:35]
	global_load_dwordx4 v[122:125], v[2:3], off
	global_load_dwordx4 v[126:129], v[2:3], off offset:32
	global_load_dwordx4 v[130:133], v[2:3], off offset:64
	global_load_dwordx4 v[134:137], v[2:3], off offset:96
	global_load_dwordx4 v[138:141], v[2:3], off offset:128
	global_load_dwordx4 v[142:145], v[2:3], off offset:160
	global_load_dwordx4 v[146:149], v[2:3], off offset:192
	global_load_dwordx4 v[154:157], v[2:3], off offset:224
	v_and_b32_e32 v6, 0xfffff0, v163
	v_lshlrev_b32_e32 v7, 1, v163
	v_and_or_b32 v6, v7, 8, v6
	v_lshrrev_b32_e32 v7, 1, v163
	v_lshrrev_b32_e32 v6, 1, v6
	v_bfe_u32 v10, v8, 5, 2
	v_and_b32_e32 v3, 3, v163
	s_movk_i32 s5, 0x70
	v_or_b32_e32 v6, v6, v10
	v_and_or_b32 v3, v7, 4, v3
	v_add_u32_e32 v7, 32, v163
	v_bitop3_b32 v5, v9, v1, s5 bitop3:0x78
	v_lshlrev_b32_e32 v2, 9, v6
	v_and_b32_e32 v6, 48, v9
	v_and_b32_e32 v9, 0xfffff0, v7
	v_lshlrev_b32_e32 v7, 1, v7
	v_and_or_b32 v7, v7, 8, v9
	v_lshrrev_b32_e32 v7, 1, v7
	v_lshlrev_b32_e32 v3, 6, v3
	v_or_b32_e32 v7, v7, v10
	v_lshlrev_b32_e32 v7, 9, v7
	v_lshlrev_b32_e32 v10, 8, v163
	v_or3_b32 v189, v2, v3, v6
	v_or3_b32 v188, v7, v3, v6
	v_add3_u32 v190, 0, v5, v10
	v_add_u32_e32 v5, 0, v189
	v_lshlrev_b32_e32 v7, 4, v1
	s_lshl_b32 s4, s25, 2
	s_add_i32 s25, s4, 0
	s_movk_i32 s4, 0x60
	v_lshlrev_b32_e32 v9, 1, v1
	v_and_b32_e32 v3, 32, v9
	v_and_b32_e32 v4, 63, v1
	v_and_b32_e32 v2, 0xc0, v7
	s_waitcnt vmcnt(11)
	ds_write_b128 v190, v[114:117] offset:32768
	s_waitcnt vmcnt(10)
	ds_write_b128 v190, v[118:121] offset:40960
	s_waitcnt vmcnt(9)
	ds_write_b128 v5, v[150:153]
	v_add_u32_e32 v5, 0, v188
	s_addk_i32 s28, 0xff40
	v_bitop3_b32 v192, v34, v7, s5 bitop3:0x78
	v_cmp_gt_u32_e64 s[38:39], 32, v4
	v_cmp_eq_u32_e64 s[40:41], 0, v4
	s_waitcnt vmcnt(8)
	ds_write_b128 v5, v[158:161]
	v_and_b32_e32 v5, 0x70, v7
	v_bitop3_b32 v195, v34, v5, s4 bitop3:0x36
	s_movk_i32 s4, 0x80
	v_bitop3_b32 v196, v34, v5, s4 bitop3:0x36
	s_movk_i32 s4, 0xa0
	v_bitop3_b32 v197, v34, v5, s4 bitop3:0x36
	s_movk_i32 s4, 0xc0
	v_bitop3_b32 v198, v34, v5, s4 bitop3:0x36
	s_movk_i32 s4, 0xe0
	v_bitop3_b32 v199, v34, v5, s4 bitop3:0x36
	s_movk_i32 s4, 0x118
	v_and_or_b32 v3, v8, s4, v3
	v_bitop3_b32 v193, v34, v5, 32 bitop3:0x36
	v_bitop3_b32 v194, v34, v5, 64 bitop3:0x36
	v_lshlrev_b32_e32 v4, 2, v187
	v_add3_u32 v200, v2, 0, v3
	v_or_b32_e32 v2, s28, v186
	v_mov_b32_e32 v34, v35
	v_mov_b32_e32 v48, v35
	v_mov_b32_e32 v49, v35
	v_sub_u32_e32 v201, v2, v4
	s_lshl_b32 s4, s21, 8
	s_lshl_b32 s31, s21, 2
	v_mov_b32_e32 v36, v35
	v_mov_b32_e32 v37, v35
	v_mov_b32_e32 v38, v35
	v_mov_b32_e32 v39, v35
	v_mov_b32_e32 v40, v35
	v_mov_b32_e32 v41, v35
	v_mov_b32_e32 v42, v35
	v_mov_b32_e32 v43, v35
	v_mov_b32_e32 v44, v35
	v_mov_b32_e32 v45, v35
	v_mov_b32_e32 v46, v35
	v_mov_b32_e32 v47, v35
	v_mov_b64_e32 v[2:3], v[34:35]
	v_mov_b64_e32 v[18:19], v[34:35]
	v_mov_b64_e32 v[64:65], v[48:49]
	v_mov_b64_e32 v[80:81], v[48:49]
	s_add_i32 s13, s13, 4
	s_ashr_i32 s24, s9, 6
	s_mov_b32 s20, 0
	s_add_i32 s25, s25, 0x10a00
	v_lshl_add_u32 v191, v186, 8, 0
	s_add_i32 s34, s4, 0x7ff
	s_add_i32 s30, s31, 31
	s_add_i32 s31, s31, 32
	v_mov_b32_e32 v202, 0
	s_mov_b64 s[4:5], 0
	v_mov_b64_e32 v[4:5], v[36:37]
	v_mov_b64_e32 v[6:7], v[38:39]
	v_mov_b64_e32 v[8:9], v[40:41]
	v_mov_b64_e32 v[10:11], v[42:43]
	v_mov_b64_e32 v[12:13], v[44:45]
	v_mov_b64_e32 v[14:15], v[46:47]
	v_mov_b64_e32 v[16:17], v[48:49]
	v_mov_b64_e32 v[20:21], v[36:37]
	v_mov_b64_e32 v[22:23], v[38:39]
	v_mov_b64_e32 v[24:25], v[40:41]
	v_mov_b64_e32 v[26:27], v[42:43]
	v_mov_b64_e32 v[28:29], v[44:45]
	v_mov_b64_e32 v[30:31], v[46:47]
	v_mov_b64_e32 v[32:33], v[48:49]
	v_mov_b64_e32 v[62:63], v[46:47]
	v_mov_b64_e32 v[60:61], v[44:45]
	v_mov_b64_e32 v[58:59], v[42:43]
	v_mov_b64_e32 v[56:57], v[40:41]
	v_mov_b64_e32 v[54:55], v[38:39]
	v_mov_b64_e32 v[52:53], v[36:37]
	v_mov_b64_e32 v[50:51], v[34:35]
	v_mov_b64_e32 v[78:79], v[46:47]
	v_mov_b64_e32 v[76:77], v[44:45]
	v_mov_b64_e32 v[74:75], v[42:43]
	v_mov_b64_e32 v[72:73], v[40:41]
	v_mov_b64_e32 v[70:71], v[38:39]
	v_mov_b64_e32 v[68:69], v[36:37]
	v_mov_b64_e32 v[66:67], v[34:35]
	s_waitcnt vmcnt(0) lgkmcnt(0)
	s_barrier
	s_cmp_eq_u32 s31, s20
	s_cbranch_scc1 .LBB0_665

.LBB0_667:
	s_lshl_b32 s53, s21, 14
	v_add_u32_e32 v34, s53, v191
	v_add_u32_e32 v40, v34, v192
	ds_read_b128 v[36:39], v40 offset:32768
	s_mov_b32 s4, 0x3e0293ee
	s_cmp_ge_i32 s34, s9
	s_cselect_b64 s[48:49], -1, 0
	s_cmp_lt_i32 s34, s9
	v_cmp_lt_i32_e64 s[46:47], 0, v201
	v_cmp_lt_i32_e64 s[44:45], 1, v201
	v_cmp_lt_i32_e64 s[42:43], 32, v201
	v_cmp_lt_i32_e32 vcc, 33, v201
	s_waitcnt lgkmcnt(0)
	v_mfma_f32_32x32x16_bf16 v[82:97], v[36:39], v[122:125], 0
	ds_read_b128 v[36:39], v40 offset:40960
	v_add_u32_e32 v40, v34, v193
	s_waitcnt lgkmcnt(0)
	v_mfma_f32_32x32x16_bf16 v[98:113], v[36:39], v[122:125], 0
	ds_read_b128 v[36:39], v40 offset:32768
	s_waitcnt lgkmcnt(0)
	v_mfma_f32_32x32x16_bf16 v[82:97], v[36:39], v[126:129], v[82:97]
	ds_read_b128 v[36:39], v40 offset:40960
	v_add_u32_e32 v40, v34, v194
	s_waitcnt lgkmcnt(0)
	v_mfma_f32_32x32x16_bf16 v[98:113], v[36:39], v[126:129], v[98:113]
	ds_read_b128 v[36:39], v40 offset:32768
	s_waitcnt lgkmcnt(0)
	v_mfma_f32_32x32x16_bf16 v[82:97], v[36:39], v[130:133], v[82:97]
	ds_read_b128 v[36:39], v40 offset:40960
	v_add_u32_e32 v40, v34, v195
	s_waitcnt lgkmcnt(0)
	v_mfma_f32_32x32x16_bf16 v[98:113], v[36:39], v[130:133], v[98:113]
	ds_read_b128 v[36:39], v40 offset:32768
	s_waitcnt lgkmcnt(0)
	v_mfma_f32_32x32x16_bf16 v[82:97], v[36:39], v[134:137], v[82:97]
	ds_read_b128 v[36:39], v40 offset:40960
	v_add_u32_e32 v40, v34, v196
	s_waitcnt lgkmcnt(0)
	v_mfma_f32_32x32x16_bf16 v[98:113], v[36:39], v[134:137], v[98:113]
	ds_read_b128 v[36:39], v40 offset:32768
	s_waitcnt lgkmcnt(0)
	v_mfma_f32_32x32x16_bf16 v[82:97], v[36:39], v[138:141], v[82:97]
	ds_read_b128 v[36:39], v40 offset:40960
	v_add_u32_e32 v40, v34, v197
	s_waitcnt lgkmcnt(0)
	v_mfma_f32_32x32x16_bf16 v[98:113], v[36:39], v[138:141], v[98:113]
	ds_read_b128 v[36:39], v40 offset:32768
	s_waitcnt lgkmcnt(0)
	v_mfma_f32_32x32x16_bf16 v[82:97], v[36:39], v[142:145], v[82:97]
	ds_read_b128 v[36:39], v40 offset:40960
	v_add_u32_e32 v40, v34, v198
	v_add_u32_e32 v34, v34, v199
	s_waitcnt lgkmcnt(0)
	v_mfma_f32_32x32x16_bf16 v[98:113], v[36:39], v[142:145], v[98:113]
	ds_read_b128 v[36:39], v40 offset:32768
	s_waitcnt lgkmcnt(0)
	v_mfma_f32_32x32x16_bf16 v[82:97], v[36:39], v[146:149], v[82:97]
	ds_read_b128 v[36:39], v40 offset:40960
	ds_read_b128 v[40:43], v34 offset:40960
	s_waitcnt lgkmcnt(1)
	v_mfma_f32_32x32x16_bf16 v[98:113], v[36:39], v[146:149], v[98:113]
	ds_read_b128 v[36:39], v34 offset:32768
	s_waitcnt lgkmcnt(0)
	v_mfma_f32_32x32x16_bf16 v[82:97], v[36:39], v[154:157], v[82:97]
	v_mfma_f32_32x32x16_bf16 v[98:113], v[40:43], v[154:157], v[98:113]
	s_nop 10
	v_mul_f32_e64 v38, v82, s4
	v_mul_f32_e64 v39, v83, s4
	v_exp_f32_e64 v40, -|v38|
	v_exp_f32_e64 v41, -|v39|
	v_max_f32_e32 v44, 0, v38
	v_max_f32_e32 v45, 0, v39
	v_pk_mul_f32 v[36:37], v[98:99], s[4:5] op_sel_hi:[1,0]
	s_nop 0
	v_exp_f32_e64 v42, -|v36|
	v_exp_f32_e64 v43, -|v37|
	v_pk_add_f32 v[40:41], v[40:41], 1.0 op_sel_hi:[1,0]
	v_pk_add_f32 v[42:43], v[42:43], 1.0 op_sel_hi:[1,0]
	v_log_f32_e32 v40, v40
	v_log_f32_e32 v41, v41
	v_log_f32_e32 v42, v42
	v_log_f32_e32 v43, v43
	v_pk_add_f32 v[44:45], v[44:45], v[40:41]
	v_max_f32_e32 v40, 0, v36
	v_max_f32_e32 v41, 0, v37
	v_pk_add_f32 v[82:83], v[40:41], v[42:43]
	s_cbranch_scc0 .Lsbd_668
